# P8 gate phase: each workgroup now gets two items of the heavier (transposing) half and two of the lighter one instead of four of one kind
# speedup vs baseline: 1.0086x; 1.0062x over previous
.LBB0_777:
	s_lshr_b32 s98, s25, 8
	s_xor_b32 s98, s98, s25
	s_and_b32 s26, s98, 1
	s_and_b32 s8, s19, 0xffffffc0
	v_add_u32_e32 v66, s8, v1
	s_lshl_b32 s0, s26, 11
	s_add_u32 s0, s3, s0
	v_ashrrev_i32_e32 v67, 31, v66
	s_addc_u32 s1, s18, 0
	v_lshlrev_b64 v[96:97], 12, v[66:67]
	v_lshl_add_u64 v[2:3], s[0:1], 0, v[96:97]
	v_lshl_add_u64 v[2:3], v[2:3], 0, v[74:75]
	global_load_dwordx4 v[62:65], v[2:3], off nt
	global_load_dwordx4 v[58:61], v[2:3], off offset:1024 nt
	v_or_b32_e32 v2, 1, v66
	v_ashrrev_i32_e32 v3, 31, v2
	v_lshlrev_b64 v[2:3], 12, v[2:3]
	v_lshl_add_u64 v[2:3], s[0:1], 0, v[2:3]
	v_lshl_add_u64 v[2:3], v[2:3], 0, v[74:75]
	global_load_dwordx4 v[54:57], v[2:3], off nt
	global_load_dwordx4 v[50:53], v[2:3], off offset:1024 nt
	v_or_b32_e32 v2, 2, v66
	v_ashrrev_i32_e32 v3, 31, v2
	v_lshlrev_b64 v[2:3], 12, v[2:3]
	v_lshl_add_u64 v[2:3], s[0:1], 0, v[2:3]
	v_lshl_add_u64 v[2:3], v[2:3], 0, v[74:75]
	global_load_dwordx4 v[46:49], v[2:3], off nt
	global_load_dwordx4 v[42:45], v[2:3], off offset:1024 nt
	v_or_b32_e32 v2, 3, v66
	v_ashrrev_i32_e32 v3, 31, v2
	v_lshlrev_b64 v[2:3], 12, v[2:3]
	v_lshl_add_u64 v[2:3], s[0:1], 0, v[2:3]
	v_lshl_add_u64 v[2:3], v[2:3], 0, v[74:75]
	global_load_dwordx4 v[38:41], v[2:3], off nt
	global_load_dwordx4 v[34:37], v[2:3], off offset:1024 nt
	v_or_b32_e32 v2, 4, v66
	v_ashrrev_i32_e32 v3, 31, v2
	v_lshlrev_b64 v[2:3], 12, v[2:3]
	v_lshl_add_u64 v[2:3], s[0:1], 0, v[2:3]
	v_lshl_add_u64 v[2:3], v[2:3], 0, v[74:75]
	global_load_dwordx4 v[30:33], v[2:3], off nt
	global_load_dwordx4 v[26:29], v[2:3], off offset:1024 nt
	v_or_b32_e32 v2, 5, v66
	v_ashrrev_i32_e32 v3, 31, v2
	v_lshlrev_b64 v[2:3], 12, v[2:3]
	v_lshl_add_u64 v[2:3], s[0:1], 0, v[2:3]
	v_lshl_add_u64 v[2:3], v[2:3], 0, v[74:75]
	global_load_dwordx4 v[22:25], v[2:3], off nt
	global_load_dwordx4 v[18:21], v[2:3], off offset:1024 nt
	v_or_b32_e32 v2, 6, v66
	v_ashrrev_i32_e32 v3, 31, v2
	v_lshlrev_b64 v[2:3], 12, v[2:3]
	v_lshl_add_u64 v[2:3], s[0:1], 0, v[2:3]
	v_lshl_add_u64 v[2:3], v[2:3], 0, v[74:75]
	global_load_dwordx4 v[14:17], v[2:3], off nt
	global_load_dwordx4 v[10:13], v[2:3], off offset:1024 nt
	v_or_b32_e32 v2, 7, v66
	v_ashrrev_i32_e32 v3, 31, v2
	v_lshlrev_b64 v[2:3], 12, v[2:3]
	v_lshl_add_u64 v[2:3], s[0:1], 0, v[2:3]
	v_lshl_add_u64 v[2:3], v[2:3], 0, v[74:75]
	global_load_dwordx4 v[6:9], v[2:3], off nt
	s_nop 0
	global_load_dwordx4 v[2:5], v[2:3], off offset:1024 nt
	s_bitcmp1_b32 s26, 0
	s_cselect_b64 s[10:11], -1, 0
	s_and_b64 vcc, exec, s[10:11]
	s_cbranch_vccnz .LBB0_779
	s_ashr_i32 s9, s8, 31
	s_lshl_b64 s[16:17], s[8:9], 1
	v_lshl_add_u64 v[72:73], v[76:77], 0, s[16:17]
	v_lshl_add_u64 v[94:95], v[78:79], 0, s[16:17]
	global_load_dwordx4 v[68:71], v[72:73], off nt
	global_load_dwordx4 v[140:143], v[94:95], off nt
	v_add_co_u32_e64 v94, s[0:1], s21, v94
	v_lshl_add_u64 v[98:99], v[80:81], 0, s[16:17]
	s_nop 0
	v_addc_co_u32_e64 v95, s[0:1], 0, v95, s[0:1]
	global_load_dwordx4 v[148:151], v[98:99], off nt
	global_load_dwordx4 v[152:155], v[94:95], off nt
	v_add_co_u32_e64 v94, s[0:1], s21, v98
	v_add_co_u32_e32 v72, vcc, 0x10000, v72
	s_nop 0
	v_addc_co_u32_e64 v95, s[0:1], 0, v99, s[0:1]
	v_addc_co_u32_e32 v73, vcc, 0, v73, vcc
	global_load_dwordx4 v[156:159], v[94:95], off nt
	global_load_dwordx4 v[160:163], v[72:73], off nt
	v_lshl_add_u64 v[72:73], v[82:83], 0, s[16:17]
	v_add_co_u32_e32 v144, vcc, s21, v72
	v_lshl_add_u64 v[94:95], v[84:85], 0, s[16:17]
	s_nop 0
	v_addc_co_u32_e32 v145, vcc, 0, v73, vcc
	global_load_dwordx4 v[164:167], v[72:73], off nt
	global_load_dwordx4 v[168:171], v[144:145], off nt
	v_add_co_u32_e32 v72, vcc, s21, v94
	v_lshl_add_u64 v[98:99], v[86:87], 0, s[16:17]
	s_nop 0
	v_addc_co_u32_e32 v73, vcc, 0, v95, vcc
	v_add_co_u32_e32 v144, vcc, s21, v98
	s_waitcnt vmcnt(0)
	v_and_b32_e32 v139, 0xffff, v141
	v_addc_co_u32_e32 v145, vcc, 0, v99, vcc
	global_load_dwordx4 v[172:175], v[94:95], off nt
	global_load_dwordx4 v[176:179], v[72:73], off nt
	global_load_dwordx4 v[180:183], v[98:99], off nt
	global_load_dwordx4 v[184:187], v[144:145], off nt
	v_and_b32_e32 v72, 0xffff, v68
	v_lshrrev_b32_e32 v68, 16, v68
	v_and_b32_e32 v73, 0xffff, v69
	v_lshrrev_b32_e32 v69, 16, v69
	v_and_b32_e32 v94, 0xffff, v70
	v_lshrrev_b32_e32 v70, 16, v70
	v_and_b32_e32 v95, 0xffff, v71
	v_lshrrev_b32_e32 v71, 16, v71
	v_and_b32_e32 v98, 0xffff, v140
	v_lshrrev_b32_e32 v99, 16, v140
	v_lshrrev_b32_e32 v140, 16, v141
	v_and_b32_e32 v141, 0xffff, v142
	v_lshrrev_b32_e32 v142, 16, v142
	v_and_b32_e32 v144, 0xffff, v143
	v_lshrrev_b32_e32 v143, 16, v143
	v_lshl_or_b32 v72, v160, 16, v72
	v_and_or_b32 v68, v160, s22, v68
	v_lshl_or_b32 v73, v161, 16, v73
	v_lshl_or_b32 v98, v152, 16, v98
	v_and_or_b32 v99, v152, s22, v99
	v_lshl_or_b32 v139, v153, 16, v139
	v_and_or_b32 v140, v153, s22, v140
	v_lshl_or_b32 v141, v154, 16, v141
	v_and_or_b32 v142, v154, s22, v142
	v_lshl_or_b32 v144, v155, 16, v144
	v_and_or_b32 v143, v155, s22, v143
	v_and_or_b32 v69, v161, s22, v69
	v_lshl_or_b32 v94, v162, 16, v94
	v_and_or_b32 v70, v162, s22, v70
	v_lshl_or_b32 v95, v163, 16, v95
	v_and_or_b32 v71, v163, s22, v71
	ds_write2st64_b32 v105, v72, v73 offset1:16
	ds_write2st64_b32 v106, v68, v69 offset0:8 offset1:24
	ds_write2st64_b32 v105, v94, v95 offset0:32 offset1:48
	ds_write2st64_b32 v106, v70, v71 offset0:40 offset1:56
	ds_write2st64_b32 v107, v98, v139 offset1:16
	ds_write2st64_b32 v108, v99, v140 offset0:8 offset1:24
	ds_write2st64_b32 v107, v141, v144 offset0:32 offset1:48
	ds_write2st64_b32 v108, v142, v143 offset0:40 offset1:56
	v_lshrrev_b32_e32 v68, 16, v148
	v_and_b32_e32 v145, 0xffff, v148
	v_and_or_b32 v94, v156, s22, v68
	v_and_b32_e32 v68, 0xffff, v149
	v_lshl_or_b32 v145, v156, 16, v145
	v_lshl_or_b32 v68, v157, 16, v68
	ds_write2st64_b32 v109, v145, v68 offset1:16
	v_lshrrev_b32_e32 v68, 16, v149
	v_and_or_b32 v95, v157, s22, v68
	v_lshl_add_u64 v[68:69], v[88:89], 0, s[16:17]
	v_add_co_u32_e32 v72, vcc, s21, v68
	s_nop 1
	v_addc_co_u32_e32 v73, vcc, 0, v69, vcc
	global_load_dwordx4 v[68:71], v[68:69], off nt
	s_nop 0
	global_load_dwordx4 v[140:143], v[72:73], off nt
	ds_write2st64_b32 v110, v94, v95 offset0:8 offset1:24
	v_and_b32_e32 v72, 0xffff, v150
	v_and_b32_e32 v94, 0xffff, v151
	v_lshl_or_b32 v72, v158, 16, v72
	v_lshl_or_b32 v94, v159, 16, v94
	v_lshrrev_b32_e32 v73, 16, v150
	ds_write2st64_b32 v109, v72, v94 offset0:32 offset1:48
	v_lshrrev_b32_e32 v72, 16, v151
	v_and_or_b32 v73, v158, s22, v73
	v_and_or_b32 v72, v159, s22, v72
	ds_write2st64_b32 v110, v73, v72 offset0:40 offset1:56
	v_and_b32_e32 v72, 0xffff, v164
	v_lshl_or_b32 v98, v168, 16, v72
	v_lshl_add_u64 v[72:73], v[90:91], 0, s[16:17]
	v_add_co_u32_e32 v94, vcc, s21, v72
	s_nop 1
	v_addc_co_u32_e32 v95, vcc, 0, v73, vcc
	global_load_dwordx4 v[148:151], v[72:73], off nt
	global_load_dwordx4 v[152:155], v[94:95], off nt
	v_and_b32_e32 v73, 0xffff, v165
	v_lshl_or_b32 v73, v169, 16, v73
	v_lshrrev_b32_e32 v72, 16, v164
	ds_write2st64_b32 v111, v98, v73 offset1:16
	v_lshrrev_b32_e32 v73, 16, v165
	v_and_or_b32 v72, v168, s22, v72
	v_and_or_b32 v73, v169, s22, v73
	ds_write2st64_b32 v112, v72, v73 offset0:8 offset1:24
	v_and_b32_e32 v72, 0xffff, v166
	v_and_b32_e32 v94, 0xffff, v167
	v_lshl_or_b32 v72, v170, 16, v72
	v_lshl_or_b32 v94, v171, 16, v94
	v_lshrrev_b32_e32 v73, 16, v166
	ds_write2st64_b32 v111, v72, v94 offset0:32 offset1:48
	v_lshrrev_b32_e32 v72, 16, v167
	v_and_or_b32 v73, v170, s22, v73
	v_and_or_b32 v72, v171, s22, v72
	ds_write2st64_b32 v112, v73, v72 offset0:40 offset1:56
	s_waitcnt vmcnt(0)
	v_and_b32_e32 v72, 0xffff, v172
	v_and_b32_e32 v94, 0xffff, v173
	v_lshl_or_b32 v72, v176, 16, v72
	v_lshl_or_b32 v94, v177, 16, v94
	v_lshrrev_b32_e32 v73, 16, v172
	ds_write2st64_b32 v113, v72, v94 offset1:16
	v_lshrrev_b32_e32 v72, 16, v173
	v_and_or_b32 v73, v176, s22, v73
	v_and_or_b32 v72, v177, s22, v72
	ds_write2st64_b32 v114, v73, v72 offset0:8 offset1:24
	v_and_b32_e32 v72, 0xffff, v174
	v_and_b32_e32 v94, 0xffff, v175
	v_lshl_or_b32 v72, v178, 16, v72
	v_lshl_or_b32 v94, v179, 16, v94
	v_lshrrev_b32_e32 v73, 16, v174
	ds_write2st64_b32 v113, v72, v94 offset0:32 offset1:48
	v_lshrrev_b32_e32 v72, 16, v175
	v_and_or_b32 v73, v178, s22, v73
	v_and_or_b32 v72, v179, s22, v72
	ds_write2st64_b32 v114, v73, v72 offset0:40 offset1:56
	v_and_b32_e32 v72, 0xffff, v180
	v_and_b32_e32 v94, 0xffff, v181
	v_lshl_or_b32 v72, v184, 16, v72
	v_lshl_or_b32 v94, v185, 16, v94
	v_lshrrev_b32_e32 v73, 16, v180
	ds_write2st64_b32 v115, v72, v94 offset1:16
	v_lshrrev_b32_e32 v72, 16, v181
	v_and_or_b32 v73, v184, s22, v73
	v_and_or_b32 v72, v185, s22, v72
	ds_write2st64_b32 v116, v73, v72 offset0:8 offset1:24
	v_and_b32_e32 v72, 0xffff, v182
	v_and_b32_e32 v94, 0xffff, v183
	v_lshl_or_b32 v72, v186, 16, v72
	v_lshl_or_b32 v94, v187, 16, v94
	v_lshrrev_b32_e32 v73, 16, v182
	ds_write2st64_b32 v115, v72, v94 offset0:32 offset1:48
	v_lshrrev_b32_e32 v72, 16, v183
	v_and_or_b32 v73, v186, s22, v73
	v_and_or_b32 v72, v187, s22, v72
	ds_write2st64_b32 v116, v73, v72 offset0:40 offset1:56
	v_and_b32_e32 v72, 0xffff, v68
	v_lshrrev_b32_e32 v68, 16, v68
	v_and_b32_e32 v73, 0xffff, v69
	v_lshrrev_b32_e32 v69, 16, v69
	v_and_or_b32 v68, v140, s22, v68
	v_and_or_b32 v69, v141, s22, v69
	ds_write2st64_b32 v118, v68, v69 offset0:8 offset1:24
	v_and_b32_e32 v68, 0xffff, v70
	v_lshrrev_b32_e32 v69, 16, v70
	v_and_b32_e32 v70, 0xffff, v71
	v_lshl_or_b32 v68, v142, 16, v68
	v_lshl_or_b32 v70, v143, 16, v70
	ds_write2st64_b32 v117, v68, v70 offset0:32 offset1:48
	v_lshrrev_b32_e32 v68, 16, v71
	v_and_or_b32 v69, v142, s22, v69
	v_and_or_b32 v68, v143, s22, v68
	ds_write2st64_b32 v118, v69, v68 offset0:40 offset1:56
	v_lshl_or_b32 v72, v140, 16, v72
	v_lshl_or_b32 v73, v141, 16, v73
	ds_write2st64_b32 v117, v72, v73 offset1:16
	v_and_b32_e32 v68, 0xffff, v148
	v_and_b32_e32 v70, 0xffff, v149
	v_lshl_or_b32 v68, v152, 16, v68
	v_lshl_or_b32 v70, v153, 16, v70
	v_lshrrev_b32_e32 v69, 16, v148
	ds_write2st64_b32 v119, v68, v70 offset1:16
	v_lshrrev_b32_e32 v68, 16, v149
	v_and_or_b32 v69, v152, s22, v69
	v_and_or_b32 v68, v153, s22, v68
	ds_write2st64_b32 v120, v69, v68 offset0:8 offset1:24
	v_and_b32_e32 v68, 0xffff, v150
	v_and_b32_e32 v70, 0xffff, v151
	v_lshl_or_b32 v68, v154, 16, v68
	v_lshl_or_b32 v70, v155, 16, v70
	v_lshrrev_b32_e32 v69, 16, v150
	ds_write2st64_b32 v119, v68, v70 offset0:32 offset1:48
	v_lshrrev_b32_e32 v68, 16, v151
	v_and_or_b32 v69, v154, s22, v69
	v_and_or_b32 v68, v155, s22, v68
	ds_write2st64_b32 v120, v69, v68 offset0:40 offset1:56
